# nt hint also on the phase-0 weight-conversion gathers (read-once f32 weights), on top of v134
# speedup vs baseline: 1.0068x; 1.0068x over previous
.LBB0_2:
	s_lshl_b32 s16, s16, 6
	s_ashr_i32 s17, s16, 31
	s_lshl_b32 s8, s15, 6
	s_lshl_b64 s[18:19], s[16:17], 2
	s_add_u32 s12, s12, s18
	s_addc_u32 s13, s13, s19
	v_or_b32_e32 v17, s8, v6
	v_lshl_add_u64 v[18:19], s[12:13], 0, v[2:3]
	v_mad_i64_i32 v[20:21], s[12:13], s10, v17, 0
	v_or_b32_e32 v17, s8, v7
	v_mad_i64_i32 v[22:23], s[12:13], s10, v17, 0
	v_or_b32_e32 v17, s8, v8
	v_mad_i64_i32 v[24:25], s[12:13], s10, v17, 0
	v_or_b32_e32 v17, s8, v9
	v_mad_i64_i32 v[26:27], s[12:13], s10, v17, 0
	v_or_b32_e32 v17, s8, v10
	v_mad_i64_i32 v[28:29], s[12:13], s10, v17, 0
	v_or_b32_e32 v17, s8, v11
	v_mad_i64_i32 v[30:31], s[12:13], s10, v17, 0
	v_or_b32_e32 v17, s8, v12
	v_mad_i64_i32 v[32:33], s[12:13], s10, v17, 0
	v_add_u32_e32 v17, s8, v13
	v_lshl_add_u64 v[20:21], v[20:21], 2, v[18:19]
	v_lshl_add_u64 v[22:23], v[22:23], 2, v[18:19]
	v_lshl_add_u64 v[24:25], v[24:25], 2, v[18:19]
	v_lshl_add_u64 v[26:27], v[26:27], 2, v[18:19]
	v_mad_i64_i32 v[34:35], s[10:11], s10, v17, 0
	v_lshl_add_u64 v[28:29], v[28:29], 2, v[18:19]
	v_lshl_add_u64 v[30:31], v[30:31], 2, v[18:19]
	v_lshl_add_u64 v[32:33], v[32:33], 2, v[18:19]
	v_lshl_add_u64 v[18:19], v[34:35], 2, v[18:19]
	global_load_dword v17, v[20:21], off nt
	s_nop 0
	global_load_dword v20, v[22:23], off nt
	global_load_dword v21, v[24:25], off nt
	s_nop 0
	global_load_dword v22, v[26:27], off nt
	global_load_dword v23, v[28:29], off nt
	global_load_dword v24, v[30:31], off nt
	global_load_dword v25, v[32:33], off nt
	s_nop 0
	global_load_dword v26, v[18:19], off nt
	v_mov_b64_e32 v[18:19], s[6:7]
	v_add_u32_e32 v27, s16, v1
	v_mad_i64_i32 v[18:19], s[6:7], v27, s2, v[18:19]
	s_ashr_i32 s9, s8, 31
	s_add_i32 s14, s14, s3
	v_lshl_add_u64 v[18:19], s[8:9], 1, v[18:19]
	s_cmpk_gt_i32 s14, 0x143f
	v_lshl_add_u64 v[28:29], v[18:19], 0, v[4:5]
	s_waitcnt vmcnt(7)
	ds_write_b32 v14, v17
	s_waitcnt vmcnt(6)
	ds_write_b32 v14, v20 offset:2080
	s_waitcnt vmcnt(5)
	ds_write_b32 v14, v21 offset:4160
	s_waitcnt vmcnt(4)
	ds_write_b32 v14, v22 offset:6240
	s_waitcnt vmcnt(3)
	ds_write_b32 v14, v23 offset:8320
	s_waitcnt vmcnt(2)
	ds_write_b32 v14, v24 offset:10400
	s_waitcnt vmcnt(1)
	ds_write_b32 v14, v25 offset:12480
	s_waitcnt vmcnt(0)
	ds_write_b32 v14, v26 offset:14560
	s_waitcnt lgkmcnt(0)
	s_barrier
	ds_read2_b32 v[20:21], v15 offset1:65
	ds_read2_b32 v[22:23], v15 offset0:130 offset1:195
	ds_read2_b32 v[24:25], v16 offset0:4 offset1:69
	ds_read2_b32 v[26:27], v16 offset0:134 offset1:199
	s_waitcnt lgkmcnt(3)
	v_cvt_pk_bf16_f32 v18, v20, v21
	s_waitcnt lgkmcnt(2)
	v_cvt_pk_bf16_f32 v19, v22, v23
	s_waitcnt lgkmcnt(1)
	v_cvt_pk_bf16_f32 v20, v24, v25
	s_waitcnt lgkmcnt(0)
	v_cvt_pk_bf16_f32 v21, v26, v27
	global_store_dwordx4 v[28:29], v[18:21], off
	s_barrier
	s_cbranch_scc1 .LBB0_7
